# lru3 carry fold: batches of 64 and 32 chunk pairs with all loads in flight
# speedup vs baseline: 1.0445x; 1.0008x over previous
; __device__ __forceinline__ void stage_lru3(const Params& P) {
;     ...
;         for (int it = gw; it < NCH * 8; it += ngw) {
;             const int c = it >> 3, h = it & 7, ch = h * 64 + lane;
;             const float* CHA = (const float*)(ws + OFF_CHA); const float* CHB = (const float*)(ws + OFF_CHB);
;             float hh = 0.f;
; #pragma unroll 1
;             for (int cb = 0; cb < c; cb += 16) {
;                 float ca[16], cbv[16];
; #pragma unroll
;                 for (int i = 0; i < 16; ++i) { const int cc = cb + i < c ? cb + i : c - 1; ca[i] = CHA[(size_t)cc * 512 + ch]; cbv[i] = CHB[(size_t)cc * 512 + ch]; }
; #pragma unroll
;                 for (int i = 0; i < 16; ++i) if (cb + i < c) hh = ca[i] * hh + cbv[i];
.Lfold64:
	s_add_i32 s0, s10, 64
	s_cmp_le_i32 s0, s8
	s_cbranch_scc0 .Lfold64_done
	s_lshl_b32 s1, s10, 11
	v_add_u32_e32 v198, s1, v0
	global_load_dword v64, v198, s[4:5]
	global_load_dword v128, v198, s[6:7]
	global_load_dword v65, v198, s[4:5] offset:2048
	global_load_dword v129, v198, s[6:7] offset:2048
	v_add_u32_e32 v200, 0x1000, v198
	global_load_dword v66, v200, s[4:5]
	global_load_dword v130, v200, s[6:7]
	global_load_dword v67, v200, s[4:5] offset:2048
	global_load_dword v131, v200, s[6:7] offset:2048
	v_add_u32_e32 v201, 0x2000, v198
	global_load_dword v68, v201, s[4:5]
	global_load_dword v132, v201, s[6:7]
	global_load_dword v69, v201, s[4:5] offset:2048
	global_load_dword v133, v201, s[6:7] offset:2048
	v_add_u32_e32 v199, 0x3000, v198
	global_load_dword v70, v199, s[4:5]
	global_load_dword v134, v199, s[6:7]
	global_load_dword v71, v199, s[4:5] offset:2048
	global_load_dword v135, v199, s[6:7] offset:2048
	v_add_u32_e32 v200, 0x4000, v198
	global_load_dword v72, v200, s[4:5]
	global_load_dword v136, v200, s[6:7]
	global_load_dword v73, v200, s[4:5] offset:2048
	global_load_dword v137, v200, s[6:7] offset:2048
	v_add_u32_e32 v201, 0x5000, v198
	global_load_dword v74, v201, s[4:5]
	global_load_dword v138, v201, s[6:7]
	global_load_dword v75, v201, s[4:5] offset:2048
	global_load_dword v139, v201, s[6:7] offset:2048
	v_add_u32_e32 v199, 0x6000, v198
	global_load_dword v76, v199, s[4:5]
	global_load_dword v140, v199, s[6:7]
	global_load_dword v77, v199, s[4:5] offset:2048
	global_load_dword v141, v199, s[6:7] offset:2048
	v_add_u32_e32 v200, 0x7000, v198
	global_load_dword v78, v200, s[4:5]
	global_load_dword v142, v200, s[6:7]
	global_load_dword v79, v200, s[4:5] offset:2048
	global_load_dword v143, v200, s[6:7] offset:2048
	v_add_u32_e32 v201, 0x8000, v198
	global_load_dword v80, v201, s[4:5]
	global_load_dword v144, v201, s[6:7]
	global_load_dword v81, v201, s[4:5] offset:2048
	global_load_dword v145, v201, s[6:7] offset:2048
	v_add_u32_e32 v199, 0x9000, v198
	global_load_dword v82, v199, s[4:5]
	global_load_dword v146, v199, s[6:7]
	global_load_dword v83, v199, s[4:5] offset:2048
	global_load_dword v147, v199, s[6:7] offset:2048
	v_add_u32_e32 v200, 0xa000, v198
	global_load_dword v84, v200, s[4:5]
	global_load_dword v148, v200, s[6:7]
	global_load_dword v85, v200, s[4:5] offset:2048
	global_load_dword v149, v200, s[6:7] offset:2048
	v_add_u32_e32 v201, 0xb000, v198
	global_load_dword v86, v201, s[4:5]
	global_load_dword v150, v201, s[6:7]
	global_load_dword v87, v201, s[4:5] offset:2048
	global_load_dword v151, v201, s[6:7] offset:2048
	v_add_u32_e32 v199, 0xc000, v198
	global_load_dword v88, v199, s[4:5]
	global_load_dword v152, v199, s[6:7]
	global_load_dword v89, v199, s[4:5] offset:2048
	global_load_dword v158, v199, s[6:7] offset:2048
	v_add_u32_e32 v200, 0xd000, v198
	global_load_dword v90, v200, s[4:5]
	global_load_dword v159, v200, s[6:7]
	global_load_dword v91, v200, s[4:5] offset:2048
	global_load_dword v160, v200, s[6:7] offset:2048
	v_add_u32_e32 v201, 0xe000, v198
	global_load_dword v92, v201, s[4:5]
	global_load_dword v161, v201, s[6:7]
	global_load_dword v93, v201, s[4:5] offset:2048
	global_load_dword v162, v201, s[6:7] offset:2048
	v_add_u32_e32 v199, 0xf000, v198
	global_load_dword v94, v199, s[4:5]
	global_load_dword v163, v199, s[6:7]
	global_load_dword v95, v199, s[4:5] offset:2048
	global_load_dword v164, v199, s[6:7] offset:2048
	v_add_u32_e32 v200, 0x10000, v198
	global_load_dword v96, v200, s[4:5]
	global_load_dword v165, v200, s[6:7]
	global_load_dword v97, v200, s[4:5] offset:2048
	global_load_dword v167, v200, s[6:7] offset:2048
	v_add_u32_e32 v201, 0x11000, v198
	global_load_dword v98, v201, s[4:5]
	global_load_dword v168, v201, s[6:7]
	global_load_dword v99, v201, s[4:5] offset:2048
	global_load_dword v169, v201, s[6:7] offset:2048
	v_add_u32_e32 v199, 0x12000, v198
	global_load_dword v100, v199, s[4:5]
	global_load_dword v170, v199, s[6:7]
	global_load_dword v101, v199, s[4:5] offset:2048
	global_load_dword v171, v199, s[6:7] offset:2048
	v_add_u32_e32 v200, 0x13000, v198
	global_load_dword v102, v200, s[4:5]
	global_load_dword v172, v200, s[6:7]
	global_load_dword v103, v200, s[4:5] offset:2048
	global_load_dword v173, v200, s[6:7] offset:2048
	v_add_u32_e32 v201, 0x14000, v198
	global_load_dword v104, v201, s[4:5]
	global_load_dword v174, v201, s[6:7]
	global_load_dword v105, v201, s[4:5] offset:2048
	global_load_dword v175, v201, s[6:7] offset:2048
	v_add_u32_e32 v199, 0x15000, v198
	global_load_dword v106, v199, s[4:5]
	global_load_dword v176, v199, s[6:7]
	global_load_dword v107, v199, s[4:5] offset:2048
	global_load_dword v177, v199, s[6:7] offset:2048
	v_add_u32_e32 v200, 0x16000, v198
	global_load_dword v108, v200, s[4:5]
	global_load_dword v178, v200, s[6:7]
	global_load_dword v109, v200, s[4:5] offset:2048
	global_load_dword v179, v200, s[6:7] offset:2048
	v_add_u32_e32 v201, 0x17000, v198
	global_load_dword v110, v201, s[4:5]
	global_load_dword v180, v201, s[6:7]
	global_load_dword v111, v201, s[4:5] offset:2048
	global_load_dword v181, v201, s[6:7] offset:2048
	v_add_u32_e32 v199, 0x18000, v198
	global_load_dword v112, v199, s[4:5]
	global_load_dword v182, v199, s[6:7]
	global_load_dword v113, v199, s[4:5] offset:2048
	global_load_dword v183, v199, s[6:7] offset:2048
	v_add_u32_e32 v200, 0x19000, v198
	global_load_dword v114, v200, s[4:5]
	global_load_dword v184, v200, s[6:7]
	global_load_dword v115, v200, s[4:5] offset:2048
	global_load_dword v185, v200, s[6:7] offset:2048
	v_add_u32_e32 v201, 0x1a000, v198
	global_load_dword v116, v201, s[4:5]
	global_load_dword v186, v201, s[6:7]
	global_load_dword v117, v201, s[4:5] offset:2048
	global_load_dword v187, v201, s[6:7] offset:2048
	v_add_u32_e32 v199, 0x1b000, v198
	global_load_dword v118, v199, s[4:5]
	global_load_dword v188, v199, s[6:7]
	global_load_dword v119, v199, s[4:5] offset:2048
	global_load_dword v189, v199, s[6:7] offset:2048
	v_add_u32_e32 v200, 0x1c000, v198
	global_load_dword v120, v200, s[4:5]
	global_load_dword v190, v200, s[6:7]
	global_load_dword v121, v200, s[4:5] offset:2048
	global_load_dword v191, v200, s[6:7] offset:2048
	v_add_u32_e32 v201, 0x1d000, v198
	global_load_dword v122, v201, s[4:5]
	global_load_dword v192, v201, s[6:7]
	global_load_dword v123, v201, s[4:5] offset:2048
	global_load_dword v193, v201, s[6:7] offset:2048
	v_add_u32_e32 v199, 0x1e000, v198
	global_load_dword v124, v199, s[4:5]
	global_load_dword v194, v199, s[6:7]
	global_load_dword v125, v199, s[4:5] offset:2048
	global_load_dword v195, v199, s[6:7] offset:2048
	v_add_u32_e32 v200, 0x1f000, v198
	global_load_dword v126, v200, s[4:5]
	global_load_dword v196, v200, s[6:7]
	global_load_dword v127, v200, s[4:5] offset:2048
	global_load_dword v197, v200, s[6:7] offset:2048
	s_waitcnt vmcnt(32)
; __device__ __forceinline__ void stage_lru3(const Params& P) {
;     ...
;             for (int cb = 0; cb < c; cb += 16) {
;                 float ca[16], cbv[16];
; #pragma unroll
;                 for (int i = 0; i < 16; ++i) { const int cc = cb + i < c ? cb + i : c - 1; ca[i] = CHA[(size_t)cc * 512 + ch]; cbv[i] = CHB[(size_t)cc * 512 + ch]; }
; #pragma unroll
;                 for (int i = 0; i < 16; ++i) if (cb + i < c) hh = ca[i] * hh + cbv[i];
	v_fmac_f32_e32 v128, v6, v64
	v_fmac_f32_e32 v129, v128, v65
	v_fmac_f32_e32 v130, v129, v66
	v_fmac_f32_e32 v131, v130, v67
	v_fmac_f32_e32 v132, v131, v68
	v_fmac_f32_e32 v133, v132, v69
	v_fmac_f32_e32 v134, v133, v70
	v_fmac_f32_e32 v135, v134, v71
	v_fmac_f32_e32 v136, v135, v72
	v_fmac_f32_e32 v137, v136, v73
	v_fmac_f32_e32 v138, v137, v74
	v_fmac_f32_e32 v139, v138, v75
	v_fmac_f32_e32 v140, v139, v76
	v_fmac_f32_e32 v141, v140, v77
	v_fmac_f32_e32 v142, v141, v78
	v_fmac_f32_e32 v143, v142, v79
	v_fmac_f32_e32 v144, v143, v80
	v_fmac_f32_e32 v145, v144, v81
	v_fmac_f32_e32 v146, v145, v82
	v_fmac_f32_e32 v147, v146, v83
	v_fmac_f32_e32 v148, v147, v84
	v_fmac_f32_e32 v149, v148, v85
	v_fmac_f32_e32 v150, v149, v86
	v_fmac_f32_e32 v151, v150, v87
	v_fmac_f32_e32 v152, v151, v88
	v_fmac_f32_e32 v158, v152, v89
	v_fmac_f32_e32 v159, v158, v90
	v_fmac_f32_e32 v160, v159, v91
	v_fmac_f32_e32 v161, v160, v92
	v_fmac_f32_e32 v162, v161, v93
	v_fmac_f32_e32 v163, v162, v94
	v_fmac_f32_e32 v164, v163, v95
	v_fmac_f32_e32 v165, v164, v96
	v_fmac_f32_e32 v167, v165, v97
	v_fmac_f32_e32 v168, v167, v98
	v_fmac_f32_e32 v169, v168, v99
	v_fmac_f32_e32 v170, v169, v100
	v_fmac_f32_e32 v171, v170, v101
	v_fmac_f32_e32 v172, v171, v102
	v_fmac_f32_e32 v173, v172, v103
	v_fmac_f32_e32 v174, v173, v104
	v_fmac_f32_e32 v175, v174, v105
	v_fmac_f32_e32 v176, v175, v106
	v_fmac_f32_e32 v177, v176, v107
	v_fmac_f32_e32 v178, v177, v108
	v_fmac_f32_e32 v179, v178, v109
	v_fmac_f32_e32 v180, v179, v110
	v_fmac_f32_e32 v181, v180, v111
	s_waitcnt vmcnt(0)
	v_fmac_f32_e32 v182, v181, v112
	v_fmac_f32_e32 v183, v182, v113
	v_fmac_f32_e32 v184, v183, v114
	v_fmac_f32_e32 v185, v184, v115
	v_fmac_f32_e32 v186, v185, v116
	v_fmac_f32_e32 v187, v186, v117
	v_fmac_f32_e32 v188, v187, v118
	v_fmac_f32_e32 v189, v188, v119
	v_fmac_f32_e32 v190, v189, v120
	v_fmac_f32_e32 v191, v190, v121
	v_fmac_f32_e32 v192, v191, v122
	v_fmac_f32_e32 v193, v192, v123
	v_fmac_f32_e32 v194, v193, v124
	v_fmac_f32_e32 v195, v194, v125
	v_fmac_f32_e32 v196, v195, v126
	v_fmac_f32_e32 v197, v196, v127
	v_mov_b32_e32 v6, v197
	s_add_i32 s10, s10, 64
	s_branch .Lfold64
.Lfold64_done:
.Lfold32:
	s_add_i32 s0, s10, 32
	s_cmp_le_i32 s0, s8
	s_cbranch_scc0 .Lfold32_done
	s_lshl_b32 s1, s10, 11
	v_add_u32_e32 v198, s1, v0
	global_load_dword v64, v198, s[4:5]
	global_load_dword v128, v198, s[6:7]
	global_load_dword v65, v198, s[4:5] offset:2048
	global_load_dword v129, v198, s[6:7] offset:2048
	v_add_u32_e32 v200, 0x1000, v198
	global_load_dword v66, v200, s[4:5]
	global_load_dword v130, v200, s[6:7]
	global_load_dword v67, v200, s[4:5] offset:2048
	global_load_dword v131, v200, s[6:7] offset:2048
	v_add_u32_e32 v201, 0x2000, v198
	global_load_dword v68, v201, s[4:5]
	global_load_dword v132, v201, s[6:7]
	global_load_dword v69, v201, s[4:5] offset:2048
	global_load_dword v133, v201, s[6:7] offset:2048
	v_add_u32_e32 v199, 0x3000, v198
	global_load_dword v70, v199, s[4:5]
	global_load_dword v134, v199, s[6:7]
	global_load_dword v71, v199, s[4:5] offset:2048
	global_load_dword v135, v199, s[6:7] offset:2048
	v_add_u32_e32 v200, 0x4000, v198
	global_load_dword v72, v200, s[4:5]
	global_load_dword v136, v200, s[6:7]
	global_load_dword v73, v200, s[4:5] offset:2048
	global_load_dword v137, v200, s[6:7] offset:2048
	v_add_u32_e32 v201, 0x5000, v198
	global_load_dword v74, v201, s[4:5]
	global_load_dword v138, v201, s[6:7]
	global_load_dword v75, v201, s[4:5] offset:2048
	global_load_dword v139, v201, s[6:7] offset:2048
	v_add_u32_e32 v199, 0x6000, v198
	global_load_dword v76, v199, s[4:5]
	global_load_dword v140, v199, s[6:7]
	global_load_dword v77, v199, s[4:5] offset:2048
	global_load_dword v141, v199, s[6:7] offset:2048
	v_add_u32_e32 v200, 0x7000, v198
	global_load_dword v78, v200, s[4:5]
	global_load_dword v142, v200, s[6:7]
	global_load_dword v79, v200, s[4:5] offset:2048
	global_load_dword v143, v200, s[6:7] offset:2048
	v_add_u32_e32 v201, 0x8000, v198
	global_load_dword v80, v201, s[4:5]
	global_load_dword v144, v201, s[6:7]
	global_load_dword v81, v201, s[4:5] offset:2048
	global_load_dword v145, v201, s[6:7] offset:2048
	v_add_u32_e32 v199, 0x9000, v198
	global_load_dword v82, v199, s[4:5]
	global_load_dword v146, v199, s[6:7]
	global_load_dword v83, v199, s[4:5] offset:2048
	global_load_dword v147, v199, s[6:7] offset:2048
	v_add_u32_e32 v200, 0xa000, v198
	global_load_dword v84, v200, s[4:5]
	global_load_dword v148, v200, s[6:7]
	global_load_dword v85, v200, s[4:5] offset:2048
	global_load_dword v149, v200, s[6:7] offset:2048
	v_add_u32_e32 v201, 0xb000, v198
	global_load_dword v86, v201, s[4:5]
	global_load_dword v150, v201, s[6:7]
	global_load_dword v87, v201, s[4:5] offset:2048
	global_load_dword v151, v201, s[6:7] offset:2048
	v_add_u32_e32 v199, 0xc000, v198
	global_load_dword v88, v199, s[4:5]
	global_load_dword v152, v199, s[6:7]
	global_load_dword v89, v199, s[4:5] offset:2048
	global_load_dword v158, v199, s[6:7] offset:2048
	v_add_u32_e32 v200, 0xd000, v198
	global_load_dword v90, v200, s[4:5]
	global_load_dword v159, v200, s[6:7]
	global_load_dword v91, v200, s[4:5] offset:2048
	global_load_dword v160, v200, s[6:7] offset:2048
	v_add_u32_e32 v201, 0xe000, v198
	global_load_dword v92, v201, s[4:5]
	global_load_dword v161, v201, s[6:7]
	global_load_dword v93, v201, s[4:5] offset:2048
	global_load_dword v162, v201, s[6:7] offset:2048
	v_add_u32_e32 v199, 0xf000, v198
	global_load_dword v94, v199, s[4:5]
	global_load_dword v163, v199, s[6:7]
	global_load_dword v95, v199, s[4:5] offset:2048
	global_load_dword v164, v199, s[6:7] offset:2048
	s_waitcnt vmcnt(16)
	v_fmac_f32_e32 v128, v6, v64
	v_fmac_f32_e32 v129, v128, v65
	v_fmac_f32_e32 v130, v129, v66
	v_fmac_f32_e32 v131, v130, v67
	v_fmac_f32_e32 v132, v131, v68
	v_fmac_f32_e32 v133, v132, v69
	v_fmac_f32_e32 v134, v133, v70
	v_fmac_f32_e32 v135, v134, v71
	v_fmac_f32_e32 v136, v135, v72
	v_fmac_f32_e32 v137, v136, v73
	v_fmac_f32_e32 v138, v137, v74
	v_fmac_f32_e32 v139, v138, v75
	v_fmac_f32_e32 v140, v139, v76
	v_fmac_f32_e32 v141, v140, v77
	v_fmac_f32_e32 v142, v141, v78
	v_fmac_f32_e32 v143, v142, v79
	v_fmac_f32_e32 v144, v143, v80
	v_fmac_f32_e32 v145, v144, v81
	v_fmac_f32_e32 v146, v145, v82
	v_fmac_f32_e32 v147, v146, v83
	v_fmac_f32_e32 v148, v147, v84
	v_fmac_f32_e32 v149, v148, v85
	v_fmac_f32_e32 v150, v149, v86
	v_fmac_f32_e32 v151, v150, v87
	s_waitcnt vmcnt(0)
	v_fmac_f32_e32 v152, v151, v88
	v_fmac_f32_e32 v158, v152, v89
	v_fmac_f32_e32 v159, v158, v90
	v_fmac_f32_e32 v160, v159, v91
	v_fmac_f32_e32 v161, v160, v92
	v_fmac_f32_e32 v162, v161, v93
	v_fmac_f32_e32 v163, v162, v94
	v_fmac_f32_e32 v164, v163, v95
	v_mov_b32_e32 v6, v164
	s_add_i32 s10, s10, 32
.Lfold32_done:
	s_cmp_lt_i32 s10, s8
	s_cbranch_scc0 .Lfold_after

; __device__ __forceinline__ void stage_lru3(const Params& P) {
;     ...
;                 for (int i = 0; i < 16; ++i) if (cb + i < c) hh = ca[i] * hh + cbv[i];
;             }
; #pragma unroll 1
;             for (int tb = c * LCH; tb < (c + 1) * LCH; tb += 16) {
.Lfold_after:
	s_lshl_b32 s12, s8, 6
	s_cmp_eq_u32 s12, 0x7fffffc0
	s_cbranch_scc1 .LBB0_232
	s_branch .LBB0_238
